# prologue x->bf16 stream with 16 loads in flight per thread
# speedup vs baseline: 1.0027x; 1.0027x over previous
.LBB0_109:
	s_or_b64 exec, exec, s[6:7]
	s_ashr_i32 s97, s96, 31
	s_lshl_b64 s[0:1], s[96:97], 9
	v_lshl_add_u64 v[2:3], s[0:1], 0, v[40:41]
	s_mov_b64 s[0:1], 0x800000
	s_ashr_i32 s31, s30, 31
	v_cmp_gt_u64_e32 vcc, s[0:1], v[2:3]
	s_and_saveexec_b64 s[6:7], vcc
	s_cbranch_execz .LBB0_112
	v_readlane_b32 s12, v254, 14
	v_readlane_b32 s13, v254, 15
	s_lshl_b64 s[8:9], s[30:31], 9
	s_lshl_b64 s[0:1], s[96:97], 13
	s_mov_b64 s[4:5], s[12:13]
	s_add_u32 s0, s4, s0
	v_readlane_b32 s14, v254, 16
	v_readlane_b32 s15, v254, 17
	s_addc_u32 s1, s5, s1
	v_lshl_add_u64 v[4:5], v[40:41], 4, s[0:1]
	s_lshl_b64 s[14:15], s[30:31], 13
	s_lshl_b64 s[0:1], s[96:97], 12
	s_add_u32 s0, s72, s0
	s_addc_u32 s1, s73, s1
	v_readlane_b32 s16, v254, 18
	v_readlane_b32 s17, v254, 19
	v_readlane_b32 s18, v254, 20
	v_readlane_b32 s19, v254, 21
	v_readlane_b32 s20, v254, 22
	v_readlane_b32 s21, v254, 23
	v_lshl_add_u64 v[6:7], v[40:41], 3, s[0:1]
	s_mov_b64 s[0:1], 0x22b00000
	v_lshl_add_u64 v[6:7], v[6:7], 0, s[0:1]
	s_lshl_b64 s[16:17], s[30:31], 12
	s_mov_b64 s[18:19], 0
	s_mov_b64 s[20:21], 0x7fffff
	v_readlane_b32 s22, v254, 24
	v_readlane_b32 s23, v254, 25
	v_readlane_b32 s24, v254, 26
	v_readlane_b32 s25, v254, 27
	v_readlane_b32 s26, v254, 28
	v_readlane_b32 s27, v254, 29
	s_cmpk_lg_i32 s30, 0x100
	s_cbranch_scc1 .LBB0_111
	s_mov_b32 s0, 4
.Lxconv_loop:
	global_load_dwordx4 v[128:131], v[4:5], off
	v_lshl_add_u64 v[4:5], v[4:5], 0, s[14:15]
	global_load_dwordx4 v[132:135], v[4:5], off
	v_lshl_add_u64 v[4:5], v[4:5], 0, s[14:15]
	global_load_dwordx4 v[136:139], v[4:5], off
	v_lshl_add_u64 v[4:5], v[4:5], 0, s[14:15]
	global_load_dwordx4 v[140:143], v[4:5], off
	v_lshl_add_u64 v[4:5], v[4:5], 0, s[14:15]
	global_load_dwordx4 v[144:147], v[4:5], off
	v_lshl_add_u64 v[4:5], v[4:5], 0, s[14:15]
	global_load_dwordx4 v[148:151], v[4:5], off
	v_lshl_add_u64 v[4:5], v[4:5], 0, s[14:15]
	global_load_dwordx4 v[152:155], v[4:5], off
	v_lshl_add_u64 v[4:5], v[4:5], 0, s[14:15]
	global_load_dwordx4 v[156:159], v[4:5], off
	v_lshl_add_u64 v[4:5], v[4:5], 0, s[14:15]
	global_load_dwordx4 v[160:163], v[4:5], off
	v_lshl_add_u64 v[4:5], v[4:5], 0, s[14:15]
	global_load_dwordx4 v[164:167], v[4:5], off
	v_lshl_add_u64 v[4:5], v[4:5], 0, s[14:15]
	global_load_dwordx4 v[168:171], v[4:5], off
	v_lshl_add_u64 v[4:5], v[4:5], 0, s[14:15]
	global_load_dwordx4 v[172:175], v[4:5], off
	v_lshl_add_u64 v[4:5], v[4:5], 0, s[14:15]
	global_load_dwordx4 v[176:179], v[4:5], off
	v_lshl_add_u64 v[4:5], v[4:5], 0, s[14:15]
	global_load_dwordx4 v[180:183], v[4:5], off
	v_lshl_add_u64 v[4:5], v[4:5], 0, s[14:15]
	global_load_dwordx4 v[184:187], v[4:5], off
	v_lshl_add_u64 v[4:5], v[4:5], 0, s[14:15]
	global_load_dwordx4 v[188:191], v[4:5], off
	v_lshl_add_u64 v[4:5], v[4:5], 0, s[14:15]
	s_waitcnt vmcnt(15)
	v_cvt_pk_bf16_f32 v128, v128, v129
	v_cvt_pk_bf16_f32 v129, v130, v131
	global_store_dwordx2 v[6:7], v[128:129], off
	v_lshl_add_u64 v[6:7], v[6:7], 0, s[16:17]
	s_waitcnt vmcnt(15)
	v_cvt_pk_bf16_f32 v132, v132, v133
	v_cvt_pk_bf16_f32 v133, v134, v135
	global_store_dwordx2 v[6:7], v[132:133], off
	v_lshl_add_u64 v[6:7], v[6:7], 0, s[16:17]
	s_waitcnt vmcnt(15)
	v_cvt_pk_bf16_f32 v136, v136, v137
	v_cvt_pk_bf16_f32 v137, v138, v139
	global_store_dwordx2 v[6:7], v[136:137], off
	v_lshl_add_u64 v[6:7], v[6:7], 0, s[16:17]
	s_waitcnt vmcnt(15)
	v_cvt_pk_bf16_f32 v140, v140, v141
	v_cvt_pk_bf16_f32 v141, v142, v143
	global_store_dwordx2 v[6:7], v[140:141], off
	v_lshl_add_u64 v[6:7], v[6:7], 0, s[16:17]
	s_waitcnt vmcnt(15)
	v_cvt_pk_bf16_f32 v144, v144, v145
	v_cvt_pk_bf16_f32 v145, v146, v147
	global_store_dwordx2 v[6:7], v[144:145], off
	v_lshl_add_u64 v[6:7], v[6:7], 0, s[16:17]
	s_waitcnt vmcnt(15)
	v_cvt_pk_bf16_f32 v148, v148, v149
	v_cvt_pk_bf16_f32 v149, v150, v151
	global_store_dwordx2 v[6:7], v[148:149], off
	v_lshl_add_u64 v[6:7], v[6:7], 0, s[16:17]
	s_waitcnt vmcnt(15)
	v_cvt_pk_bf16_f32 v152, v152, v153
	v_cvt_pk_bf16_f32 v153, v154, v155
	global_store_dwordx2 v[6:7], v[152:153], off
	v_lshl_add_u64 v[6:7], v[6:7], 0, s[16:17]
	s_waitcnt vmcnt(15)
	v_cvt_pk_bf16_f32 v156, v156, v157
	v_cvt_pk_bf16_f32 v157, v158, v159
	global_store_dwordx2 v[6:7], v[156:157], off
	v_lshl_add_u64 v[6:7], v[6:7], 0, s[16:17]
	s_waitcnt vmcnt(15)
	v_cvt_pk_bf16_f32 v160, v160, v161
	v_cvt_pk_bf16_f32 v161, v162, v163
	global_store_dwordx2 v[6:7], v[160:161], off
	v_lshl_add_u64 v[6:7], v[6:7], 0, s[16:17]
	s_waitcnt vmcnt(15)
	v_cvt_pk_bf16_f32 v164, v164, v165
	v_cvt_pk_bf16_f32 v165, v166, v167
	global_store_dwordx2 v[6:7], v[164:165], off
	v_lshl_add_u64 v[6:7], v[6:7], 0, s[16:17]
	s_waitcnt vmcnt(15)
	v_cvt_pk_bf16_f32 v168, v168, v169
	v_cvt_pk_bf16_f32 v169, v170, v171
	global_store_dwordx2 v[6:7], v[168:169], off
	v_lshl_add_u64 v[6:7], v[6:7], 0, s[16:17]
	s_waitcnt vmcnt(15)
	v_cvt_pk_bf16_f32 v172, v172, v173
	v_cvt_pk_bf16_f32 v173, v174, v175
	global_store_dwordx2 v[6:7], v[172:173], off
	v_lshl_add_u64 v[6:7], v[6:7], 0, s[16:17]
	s_waitcnt vmcnt(15)
	v_cvt_pk_bf16_f32 v176, v176, v177
	v_cvt_pk_bf16_f32 v177, v178, v179
	global_store_dwordx2 v[6:7], v[176:177], off
	v_lshl_add_u64 v[6:7], v[6:7], 0, s[16:17]
	s_waitcnt vmcnt(15)
	v_cvt_pk_bf16_f32 v180, v180, v181
	v_cvt_pk_bf16_f32 v181, v182, v183
	global_store_dwordx2 v[6:7], v[180:181], off
	v_lshl_add_u64 v[6:7], v[6:7], 0, s[16:17]
	s_waitcnt vmcnt(15)
	v_cvt_pk_bf16_f32 v184, v184, v185
	v_cvt_pk_bf16_f32 v185, v186, v187
	global_store_dwordx2 v[6:7], v[184:185], off
	v_lshl_add_u64 v[6:7], v[6:7], 0, s[16:17]
	s_waitcnt vmcnt(15)
	v_cvt_pk_bf16_f32 v188, v188, v189
	v_cvt_pk_bf16_f32 v189, v190, v191
	global_store_dwordx2 v[6:7], v[188:189], off
	v_lshl_add_u64 v[6:7], v[6:7], 0, s[16:17]
	s_add_i32 s0, s0, -1
	s_cmp_lg_u32 s0, 0
	s_cbranch_scc1 .Lxconv_loop
	s_branch .LBB0_112
